# adds: pass-2 accumulator zero-init moved off the fast path; selected-loop step prologue issues K fragment reads right after the barrier and merges the two mask-word LDS reads
# speedup vs baseline: 1.0499x; 1.0068x over previous
.Lp2_zero_e:
	v_mov_b32_e32 v56, 0
	v_mov_b32_e32 v57, 0
	v_mov_b32_e32 v58, 0
	v_mov_b32_e32 v59, 0
	v_mov_b32_e32 v52, 0
	v_mov_b32_e32 v53, 0
	v_mov_b32_e32 v54, 0
	v_mov_b32_e32 v55, 0
	v_mov_b32_e32 v44, 0
	v_mov_b32_e32 v45, 0
	v_mov_b32_e32 v46, 0
	v_mov_b32_e32 v47, 0
	v_mov_b32_e32 v48, 0
	v_mov_b32_e32 v49, 0
	v_mov_b32_e32 v50, 0
	v_mov_b32_e32 v51, 0
	s_branch .LBB0_747

.LBB0_745:
	s_add_i32 s2, s16, 0xfffffc00
	s_cmp_ge_i32 s13, s2
	s_cselect_b64 s[4:5], -1, 0
	s_cmp_lt_i32 s13, s2
	s_cbranch_scc1 .Lp2_zero_e
	s_movk_i32 s2, 0x3c1
	v_add3_u32 v44, v81, v90, s2
	v_cvt_f32_i32_e32 v44, v44
	s_mov_b32 s6, 2.0
	s_mov_b32 s7, 0x40400000
	v_fma_f32 v48, -v96, v44, -v89
	v_pk_fma_f32 v[54:55], v[60:61], s[6:7], v[48:49] op_sel_hi:[1,1,0]
	s_mov_b32 s6, 0x41800000
	s_mov_b32 s7, 0x41880000
	v_fma_f32 v52, 0, v60, v48
	v_add_f32_e32 v53, v60, v48
	v_pk_fma_f32 v[58:59], v[70:71], s[90:91], v[48:49] op_sel_hi:[1,1,0]
	v_pk_fma_f32 v[56:57], v[68:69], s[6:7], v[48:49] op_sel_hi:[1,1,0]
	v_pk_fma_f32 v[46:47], v[70:71], s[92:93], v[48:49] op_sel_hi:[1,1,0]
	v_pk_fma_f32 v[44:45], v[68:69], s[34:35], v[48:49] op_sel_hi:[1,1,0]
	v_pk_fma_f32 v[50:51], v[70:71], s[22:23], v[48:49] op_sel_hi:[1,1,0]
	v_pk_fma_f32 v[48:49], v[68:69], s[72:73], v[48:49] op_sel_hi:[1,1,0]

.LBB0_764:
	s_cmp_ge_i32 s13, s16
	s_cselect_b64 s[4:5], -1, 0
	s_cmp_lt_i32 s13, s16
	s_cbranch_scc1 .Lp2_zero_o
	s_movk_i32 s2, 0xffc1
	v_add3_u32 v44, v81, v90, s2
	v_cvt_f32_i32_e32 v44, v44
	s_mov_b32 s6, 2.0
	s_mov_b32 s7, 0x40400000
	v_fma_f32 v48, -v96, v44, -v89
	v_pk_fma_f32 v[54:55], v[60:61], s[6:7], v[48:49] op_sel_hi:[1,1,0]
	s_mov_b32 s6, 0x41800000
	s_mov_b32 s7, 0x41880000
	v_fma_f32 v52, 0, v60, v48
	v_add_f32_e32 v53, v60, v48
	v_pk_fma_f32 v[58:59], v[70:71], s[90:91], v[48:49] op_sel_hi:[1,1,0]
	v_pk_fma_f32 v[56:57], v[68:69], s[6:7], v[48:49] op_sel_hi:[1,1,0]
	v_pk_fma_f32 v[46:47], v[70:71], s[92:93], v[48:49] op_sel_hi:[1,1,0]
	v_pk_fma_f32 v[44:45], v[68:69], s[34:35], v[48:49] op_sel_hi:[1,1,0]
	v_pk_fma_f32 v[50:51], v[70:71], s[22:23], v[48:49] op_sel_hi:[1,1,0]
	v_pk_fma_f32 v[48:49], v[68:69], s[72:73], v[48:49] op_sel_hi:[1,1,0]

.LBB0_972:
	v_mov_b32_e32 v60, s14
	ds_read_b32 v60, v60 offset:12
	ds_read_b128 v[160:163], v118
	ds_read_b128 v[164:167], v118 offset:64
	ds_read_b128 v[168:171], v118 offset:2304
	ds_read_b128 v[172:175], v118 offset:2368
	ds_read_b128 v[176:179], v118 offset:4608
	ds_read_b128 v[180:183], v118 offset:4672
	ds_read_b128 v[184:187], v118 offset:6912
	ds_read_b128 v[188:191], v118 offset:6976
	s_waitcnt lgkmcnt(8)
	v_ashrrev_i32_e32 v62, 5, v60
	v_lshlrev_b32_e32 v61, 2, v62
	v_add_u32_e32 v61, s13, v61
	ds_read_b32 v63, v61
	v_lshl_add_u32 v62, v62, 2, v105
	ds_read_b32 v62, v62 offset:8256
	v_lshlrev_b32_e64 v61, v60, 1
	s_waitcnt lgkmcnt(0)
	v_and_b32_e32 v63, v61, v63
	v_cmp_eq_u32_e32 vcc, 0, v63
	s_cbranch_vccnz .LBB0_982
	v_lshlrev_b32_e32 v108, 6, v60
	v_cmp_le_i32_e32 vcc, s51, v60
	s_and_b64 vcc, exec, vcc
	s_mov_b64 s[4:5], -1
	v_and_b32_e32 v60, v62, v61
	v_cmp_ne_u32_e64 s[8:9], 0, v60
	s_cbranch_vccz .LBB0_977
	ds_read_b128 v[60:63], v118
	ds_read_b128 v[64:67], v118 offset:64
	v_sub_u32_e32 v109, v103, v108
	v_mov_b32_e32 v131, v107
	s_waitcnt lgkmcnt(1)
	v_mfma_f32_16x16x32_bf16 v[60:63], v[60:63], v[4:7], 0
	ds_read_b128 v[72:75], v118 offset:6976
	s_waitcnt lgkmcnt(1)
	v_mfma_f32_16x16x32_bf16 v[76:79], v[64:67], v[8:11], v[60:63]
	ds_read_b128 v[64:67], v118 offset:2368
	s_nop 3
	ds_read_b128 v[60:63], v118 offset:2304
	s_waitcnt lgkmcnt(0)
	v_mfma_f32_16x16x32_bf16 v[60:63], v[60:63], v[4:7], 0
	v_mfma_f32_16x16x32_bf16 v[68:71], v[64:67], v[8:11], v[60:63]
	ds_read_b128 v[64:67], v118 offset:4672
	s_nop 5
	ds_read_b128 v[60:63], v118 offset:4608
	s_waitcnt lgkmcnt(0)
	v_mfma_f32_16x16x32_bf16 v[60:63], v[60:63], v[4:7], 0
	v_mfma_f32_16x16x32_bf16 v[64:67], v[64:67], v[8:11], v[60:63]
	s_nop 6
	ds_read_b128 v[60:63], v118 offset:6912
	s_waitcnt lgkmcnt(0)
	v_mfma_f32_16x16x32_bf16 v[60:63], v[60:63], v[4:7], 0
	v_mfma_f32_16x16x32_bf16 v[60:63], v[72:75], v[8:11], v[60:63]
	v_sub_u32_e32 v72, v109, v98
	v_cvt_f32_u32_e32 v73, v72
	v_cmp_gt_u32_e32 vcc, 2.0, v72
	s_and_b64 vcc, vcc, s[8:9]
	v_sub_u32_e32 v74, v109, v102
	v_fma_f32 v73, -v96, v73, v76
	v_cndmask_b32_e32 v76, v249, v73, vcc
	v_add_u32_e32 v73, v109, v99
	v_cmp_gt_u32_e32 vcc, 2.0, v73
	v_cvt_f32_u32_e32 v73, v73
	s_and_b64 vcc, vcc, s[8:9]
	v_fma_f32 v73, -v96, v73, v77
	v_cndmask_b32_e32 v77, v249, v73, vcc
	v_cmp_gt_u32_e32 vcc, 2.0, v74
	v_cvt_f32_u32_e32 v74, v74
	s_and_b64 vcc, vcc, s[8:9]
	v_max3_f32 v73, v76, s36, v77
	v_fma_f32 v74, -v96, v74, v78
	v_cndmask_b32_e32 v78, v249, v74, vcc
	v_sub_u32_e32 v74, v109, v101
	v_cmp_gt_u32_e32 vcc, 2.0, v74
	v_cvt_f32_u32_e32 v74, v74
	s_and_b64 vcc, vcc, s[8:9]
	v_mov_b32_e32 v109, v106
	v_fma_f32 v74, -v96, v74, v79
	v_cndmask_b32_e32 v79, v249, v74, vcc
	v_add_u32_e32 v74, -16, v72
	v_cmp_gt_u32_e32 vcc, 2.0, v74
	v_cvt_f32_u32_e32 v74, v74
	s_and_b64 vcc, vcc, s[8:9]
	v_max3_f32 v73, v73, v78, v79
	v_fma_f32 v68, -v96, v74, v68
	v_cndmask_b32_e32 v110, v249, v68, vcc
	v_subrev_u32_e32 v68, 17, v72
	v_cmp_gt_u32_e32 vcc, 2.0, v68
	v_cvt_f32_u32_e32 v68, v68
	s_and_b64 vcc, vcc, s[8:9]
	v_fma_f32 v68, -v96, v68, v69
	v_subrev_u32_e32 v69, 18, v72
	v_cndmask_b32_e32 v111, v249, v68, vcc
	v_cmp_gt_u32_e32 vcc, 2.0, v69
	v_cvt_f32_u32_e32 v69, v69
	s_and_b64 vcc, vcc, s[8:9]
	v_max3_f32 v68, v73, v110, v111
	v_fma_f32 v69, -v96, v69, v70
	v_cndmask_b32_e32 v121, v249, v69, vcc
	v_subrev_u32_e32 v69, 19, v72
	v_cmp_gt_u32_e32 vcc, 2.0, v69
	v_cvt_f32_u32_e32 v69, v69
	s_and_b64 vcc, vcc, s[8:9]
	v_fma_f32 v69, -v96, v69, v71
	v_cndmask_b32_e32 v122, v249, v69, vcc
	v_subrev_u32_e32 v69, 32, v72
	v_cmp_gt_u32_e32 vcc, 2.0, v69
	v_cvt_f32_u32_e32 v69, v69
	s_and_b64 vcc, vcc, s[8:9]
	v_max3_f32 v68, v68, v121, v122
	v_fma_f32 v64, -v96, v69, v64
	v_cndmask_b32_e32 v123, v249, v64, vcc
	v_subrev_u32_e32 v64, 33, v72
	v_cmp_gt_u32_e32 vcc, 2.0, v64
	v_cvt_f32_u32_e32 v64, v64
	s_and_b64 vcc, vcc, s[8:9]
	v_fma_f32 v64, -v96, v64, v65
	v_subrev_u32_e32 v65, 34, v72
	v_cndmask_b32_e32 v124, v249, v64, vcc
	v_cmp_gt_u32_e32 vcc, 2.0, v65
	v_cvt_f32_u32_e32 v65, v65
	s_and_b64 vcc, vcc, s[8:9]
	v_max3_f32 v64, v68, v123, v124
	v_mov_b64_e32 v[70:71], v[38:39]
	v_fma_f32 v65, -v96, v65, v66
	v_cndmask_b32_e32 v125, v249, v65, vcc
	v_subrev_u32_e32 v65, 35, v72
	v_cmp_gt_u32_e32 vcc, 2.0, v65
	v_cvt_f32_u32_e32 v65, v65
	s_and_b64 vcc, vcc, s[8:9]
	v_mov_b64_e32 v[68:69], v[36:37]
	v_fma_f32 v65, -v96, v65, v67
	v_cndmask_b32_e32 v126, v249, v65, vcc
	v_subrev_u32_e32 v65, 48, v72
	v_cmp_gt_u32_e32 vcc, 2.0, v65
	v_cvt_f32_u32_e32 v65, v65
	s_and_b64 vcc, vcc, s[8:9]
	v_max3_f32 v64, v64, v125, v126
	v_fma_f32 v60, -v96, v65, v60
	v_cndmask_b32_e32 v127, v249, v60, vcc
	v_subrev_u32_e32 v60, 49, v72
	v_cmp_gt_u32_e32 vcc, 2.0, v60
	v_cvt_f32_u32_e32 v60, v60
	s_and_b64 vcc, vcc, s[8:9]
	v_fma_f32 v60, -v96, v60, v61
	v_subrev_u32_e32 v61, 50, v72
	v_cndmask_b32_e32 v128, v249, v60, vcc
	v_cmp_gt_u32_e32 vcc, 2.0, v61
	v_cvt_f32_u32_e32 v61, v61
	s_and_b64 vcc, vcc, s[8:9]
	v_max3_f32 v60, v64, v127, v128
	v_mov_b64_e32 v[66:67], v[34:35]
	v_fma_f32 v61, -v96, v61, v62
	v_cndmask_b32_e32 v129, v249, v61, vcc
	v_subrev_u32_e32 v61, 51, v72
	v_cmp_gt_u32_e32 vcc, 2.0, v61
	v_cvt_f32_u32_e32 v61, v61
	s_and_b64 vcc, vcc, s[8:9]
	v_mov_b64_e32 v[74:75], v[42:43]
	v_mov_b64_e32 v[64:65], v[32:33]
	v_fma_f32 v61, -v96, v61, v63
	v_cndmask_b32_e32 v130, v249, v61, vcc
	v_max3_f32 v132, v60, v129, v130
	v_mov_b64_e32 v[62:63], v[30:31]
	v_cmp_gt_f32_e32 vcc, v132, v106
	v_mov_b64_e32 v[60:61], v[28:29]
	v_mov_b64_e32 v[72:73], v[40:41]
	s_cbranch_vccz .LBB0_976
	ds_bpermute_b32 v60, v115, v132
	v_max_f32_e32 v61, v132, v132
	s_waitcnt lgkmcnt(0)
	v_max_f32_e32 v60, v60, v60
	v_max_f32_e32 v60, v61, v60
	ds_bpermute_b32 v61, v114, v60
	s_waitcnt lgkmcnt(0)
	v_max3_f32 v109, v106, v60, v61
	v_sub_f32_e32 v60, v106, v109
	v_exp_f32_e32 v60, v60
	s_nop 0
	v_mul_f32_e32 v131, v107, v60
	v_pk_mul_f32 v[74:75], v[42:43], v[60:61] op_sel_hi:[1,0]
	v_pk_mul_f32 v[72:73], v[40:41], v[60:61] op_sel_hi:[1,0]
	v_pk_mul_f32 v[70:71], v[38:39], v[60:61] op_sel_hi:[1,0]
	v_pk_mul_f32 v[68:69], v[36:37], v[60:61] op_sel_hi:[1,0]
	v_pk_mul_f32 v[66:67], v[34:35], v[60:61] op_sel_hi:[1,0]
	v_pk_mul_f32 v[64:65], v[32:33], v[60:61] op_sel_hi:[1,0]
	v_pk_mul_f32 v[62:63], v[30:31], v[60:61] op_sel_hi:[1,0]
	v_pk_mul_f32 v[60:61], v[28:29], v[60:61] op_sel_hi:[1,0]

.LBB0_977:
	s_and_b64 vcc, exec, s[4:5]
	s_cbranch_vccz .LBB0_981
	s_nop 5
	v_or_b32_e32 v60, v98, v108
	v_sub_u32_e32 v60, v103, v60
	v_cvt_f32_i32_e32 v60, v60
	s_mov_b32 s4, 2.0
	s_mov_b32 s5, 0x40400000
	v_fma_f32 v60, -v96, v60, -v106
	v_cndmask_b32_e64 v68, v249, v60, s[8:9]
	v_pk_fma_f32 v[62:63], v[96:97], s[4:5], v[68:69] op_sel_hi:[1,1,0]
	s_mov_b32 s4, 0x41800000
	s_mov_b32 s5, 0x41880000
	v_fma_f32 v60, 0, v96, v68
	v_add_f32_e32 v61, v96, v68
	v_pk_fma_f32 v[66:67], v[90:91], s[90:91], v[68:69] op_sel_hi:[1,1,0]
	v_pk_fma_f32 v[64:65], v[88:89], s[4:5], v[68:69] op_sel_hi:[1,1,0]
	v_pk_fma_f32 v[78:79], v[90:91], s[92:93], v[68:69] op_sel_hi:[1,1,0]
	v_pk_fma_f32 v[76:77], v[88:89], s[34:35], v[68:69] op_sel_hi:[1,1,0]
	v_pk_fma_f32 v[110:111], v[90:91], s[22:23], v[68:69] op_sel_hi:[1,1,0]
	v_pk_fma_f32 v[108:109], v[88:89], s[72:73], v[68:69] op_sel_hi:[1,1,0]
	s_waitcnt lgkmcnt(7)
	v_mfma_f32_16x16x32_bf16 v[60:63], v[160:163], v[4:7], v[60:63]
	s_waitcnt lgkmcnt(6)
	v_mfma_f32_16x16x32_bf16 v[72:75], v[164:167], v[8:11], v[60:63]
	ds_read_b128 v[196:199], v243
	ds_read_b128 v[200:203], v243 offset:64
	s_waitcnt lgkmcnt(7)
	v_mfma_f32_16x16x32_bf16 v[60:63], v[168:171], v[4:7], v[64:67]
	s_waitcnt lgkmcnt(6)
	v_mfma_f32_16x16x32_bf16 v[68:71], v[172:175], v[8:11], v[60:63]
	ds_read_b128 v[204:207], v243 offset:2304
	ds_read_b128 v[208:211], v243 offset:2368
	s_waitcnt lgkmcnt(7)
	v_mfma_f32_16x16x32_bf16 v[60:63], v[176:179], v[4:7], v[76:79]
	s_waitcnt lgkmcnt(6)
	v_mfma_f32_16x16x32_bf16 v[60:63], v[180:183], v[8:11], v[60:63]
	ds_read_b128 v[212:215], v243 offset:4608
	ds_read_b128 v[216:219], v243 offset:4672
	s_waitcnt lgkmcnt(7)
	v_mfma_f32_16x16x32_bf16 v[64:67], v[184:187], v[4:7], v[108:111]
	s_waitcnt lgkmcnt(6)
	v_mfma_f32_16x16x32_bf16 v[64:67], v[188:191], v[8:11], v[64:67]
	ds_read_b128 v[220:223], v243 offset:6912
	ds_read_b128 v[224:227], v243 offset:6976
	v_max3_f32 v76, v72, s36, v73
	v_max3_f32 v76, v76, v74, v75
	v_max3_f32 v76, v76, v68, v69
	v_max3_f32 v76, v76, v70, v71
	v_max3_f32 v76, v76, v60, v61
	v_max3_f32 v76, v76, v62, v63
	s_nop 1
	v_max3_f32 v76, v76, v64, v65
	v_max3_f32 v76, v76, v66, v67
	v_cmp_lt_f32_e32 vcc, 0, v76
	s_cbranch_vccz .LBB0_980
	ds_bpermute_b32 v77, v115, v76
	v_max_f32_e32 v76, v76, v76
	s_waitcnt lgkmcnt(0)
	v_max_f32_e32 v77, v77, v77
	v_max_f32_e32 v76, v76, v77
	ds_bpermute_b32 v77, v114, v76
	s_waitcnt lgkmcnt(0)
	v_max3_f32 v77, 0, v76, v77
	v_sub_f32_e32 v76, 0, v77
	v_exp_f32_e32 v76, v76
	v_add_f32_e32 v106, v106, v77
	v_mul_f32_e32 v107, v107, v76
	v_pk_mul_f32 v[42:43], v[42:43], v[76:77] op_sel_hi:[1,0]
	v_pk_mul_f32 v[40:41], v[40:41], v[76:77] op_sel_hi:[1,0]
	v_pk_mul_f32 v[38:39], v[38:39], v[76:77] op_sel_hi:[1,0]
	v_pk_mul_f32 v[36:37], v[36:37], v[76:77] op_sel_hi:[1,0]
	v_pk_mul_f32 v[34:35], v[34:35], v[76:77] op_sel_hi:[1,0]
	v_pk_mul_f32 v[32:33], v[32:33], v[76:77] op_sel_hi:[1,0]
	v_pk_mul_f32 v[30:31], v[30:31], v[76:77] op_sel_hi:[1,0]
	v_pk_mul_f32 v[28:29], v[28:29], v[76:77] op_sel_hi:[1,0]
	v_sub_f32_e32 v72, v72, v77
	v_sub_f32_e32 v73, v73, v77
	v_sub_f32_e32 v74, v74, v77
	v_sub_f32_e32 v75, v75, v77
	v_sub_f32_e32 v68, v68, v77
	v_sub_f32_e32 v69, v69, v77
	v_sub_f32_e32 v70, v70, v77
	v_sub_f32_e32 v71, v71, v77
	v_sub_f32_e32 v60, v60, v77
	v_sub_f32_e32 v61, v61, v77
	v_sub_f32_e32 v62, v62, v77
	v_sub_f32_e32 v63, v63, v77
	v_sub_f32_e32 v64, v64, v77
	v_sub_f32_e32 v65, v65, v77
	v_sub_f32_e32 v66, v66, v77
	v_sub_f32_e32 v67, v67, v77

.LBB0_987:
	s_xor_b32 s2, s16, 0x3ffffffe
	s_lshl_b32 s2, s2, 2
	s_add_i32 s2, s12, s2
	v_mov_b32_e32 v60, s2
	ds_read_b32 v60, v60
	ds_read_b128 v[160:163], v119
	ds_read_b128 v[164:167], v119 offset:64
	ds_read_b128 v[168:171], v119 offset:2304
	ds_read_b128 v[172:175], v119 offset:2368
	ds_read_b128 v[176:179], v119 offset:4608
	ds_read_b128 v[180:183], v119 offset:4672
	ds_read_b128 v[184:187], v119 offset:6912
	ds_read_b128 v[188:191], v119 offset:6976
	s_waitcnt lgkmcnt(8)
	v_ashrrev_i32_e32 v62, 5, v60
	v_lshlrev_b32_e32 v61, 2, v62
	v_add_u32_e32 v61, s13, v61
	ds_read_b32 v63, v61
	v_lshl_add_u32 v62, v62, 2, v105
	ds_read_b32 v62, v62 offset:8256
	v_lshlrev_b32_e64 v61, v60, 1
	s_waitcnt lgkmcnt(0)
	v_and_b32_e32 v63, v61, v63
	v_cmp_eq_u32_e32 vcc, 0, v63
	s_cbranch_vccnz .LBB0_997
	v_lshlrev_b32_e32 v108, 6, v60
	v_cmp_le_i32_e32 vcc, s51, v60
	s_and_b64 vcc, exec, vcc
	s_mov_b64 s[4:5], -1
	v_and_b32_e32 v60, v62, v61
	v_cmp_ne_u32_e64 s[8:9], 0, v60
	s_cbranch_vccz .LBB0_992
	ds_read_b128 v[60:63], v119
	ds_read_b128 v[64:67], v119 offset:64
	v_sub_u32_e32 v109, v103, v108
	v_mov_b32_e32 v131, v107
	s_waitcnt lgkmcnt(1)
	v_mfma_f32_16x16x32_bf16 v[60:63], v[60:63], v[4:7], 0
	ds_read_b128 v[72:75], v119 offset:6976
	s_waitcnt lgkmcnt(1)
	v_mfma_f32_16x16x32_bf16 v[76:79], v[64:67], v[8:11], v[60:63]
	ds_read_b128 v[64:67], v119 offset:2368
	s_nop 3
	ds_read_b128 v[60:63], v119 offset:2304
	s_waitcnt lgkmcnt(0)
	v_mfma_f32_16x16x32_bf16 v[60:63], v[60:63], v[4:7], 0
	v_mfma_f32_16x16x32_bf16 v[68:71], v[64:67], v[8:11], v[60:63]
	ds_read_b128 v[64:67], v119 offset:4672
	s_nop 5
	ds_read_b128 v[60:63], v119 offset:4608
	s_waitcnt lgkmcnt(0)
	v_mfma_f32_16x16x32_bf16 v[60:63], v[60:63], v[4:7], 0
	v_mfma_f32_16x16x32_bf16 v[64:67], v[64:67], v[8:11], v[60:63]
	s_nop 6
	ds_read_b128 v[60:63], v119 offset:6912
	s_waitcnt lgkmcnt(0)
	v_mfma_f32_16x16x32_bf16 v[60:63], v[60:63], v[4:7], 0
	v_mfma_f32_16x16x32_bf16 v[60:63], v[72:75], v[8:11], v[60:63]
	v_sub_u32_e32 v72, v109, v98
	v_cvt_f32_u32_e32 v73, v72
	v_cmp_gt_u32_e32 vcc, 2.0, v72
	s_and_b64 vcc, vcc, s[8:9]
	v_sub_u32_e32 v74, v109, v102
	v_fma_f32 v73, -v96, v73, v76
	v_cndmask_b32_e32 v76, v249, v73, vcc
	v_add_u32_e32 v73, v109, v99
	v_cmp_gt_u32_e32 vcc, 2.0, v73
	v_cvt_f32_u32_e32 v73, v73
	s_and_b64 vcc, vcc, s[8:9]
	v_fma_f32 v73, -v96, v73, v77
	v_cndmask_b32_e32 v77, v249, v73, vcc
	v_cmp_gt_u32_e32 vcc, 2.0, v74
	v_cvt_f32_u32_e32 v74, v74
	s_and_b64 vcc, vcc, s[8:9]
	v_max3_f32 v73, v76, s36, v77
	v_fma_f32 v74, -v96, v74, v78
	v_cndmask_b32_e32 v78, v249, v74, vcc
	v_sub_u32_e32 v74, v109, v101
	v_cmp_gt_u32_e32 vcc, 2.0, v74
	v_cvt_f32_u32_e32 v74, v74
	s_and_b64 vcc, vcc, s[8:9]
	v_mov_b32_e32 v109, v106
	v_fma_f32 v74, -v96, v74, v79
	v_cndmask_b32_e32 v79, v249, v74, vcc
	v_add_u32_e32 v74, -16, v72
	v_cmp_gt_u32_e32 vcc, 2.0, v74
	v_cvt_f32_u32_e32 v74, v74
	s_and_b64 vcc, vcc, s[8:9]
	v_max3_f32 v73, v73, v78, v79
	v_fma_f32 v68, -v96, v74, v68
	v_cndmask_b32_e32 v110, v249, v68, vcc
	v_subrev_u32_e32 v68, 17, v72
	v_cmp_gt_u32_e32 vcc, 2.0, v68
	v_cvt_f32_u32_e32 v68, v68
	s_and_b64 vcc, vcc, s[8:9]
	v_fma_f32 v68, -v96, v68, v69
	v_subrev_u32_e32 v69, 18, v72
	v_cndmask_b32_e32 v111, v249, v68, vcc
	v_cmp_gt_u32_e32 vcc, 2.0, v69
	v_cvt_f32_u32_e32 v69, v69
	s_and_b64 vcc, vcc, s[8:9]
	v_max3_f32 v68, v73, v110, v111
	v_fma_f32 v69, -v96, v69, v70
	v_cndmask_b32_e32 v121, v249, v69, vcc
	v_subrev_u32_e32 v69, 19, v72
	v_cmp_gt_u32_e32 vcc, 2.0, v69
	v_cvt_f32_u32_e32 v69, v69
	s_and_b64 vcc, vcc, s[8:9]
	v_fma_f32 v69, -v96, v69, v71
	v_cndmask_b32_e32 v122, v249, v69, vcc
	v_subrev_u32_e32 v69, 32, v72
	v_cmp_gt_u32_e32 vcc, 2.0, v69
	v_cvt_f32_u32_e32 v69, v69
	s_and_b64 vcc, vcc, s[8:9]
	v_max3_f32 v68, v68, v121, v122
	v_fma_f32 v64, -v96, v69, v64
	v_cndmask_b32_e32 v123, v249, v64, vcc
	v_subrev_u32_e32 v64, 33, v72
	v_cmp_gt_u32_e32 vcc, 2.0, v64
	v_cvt_f32_u32_e32 v64, v64
	s_and_b64 vcc, vcc, s[8:9]
	v_fma_f32 v64, -v96, v64, v65
	v_subrev_u32_e32 v65, 34, v72
	v_cndmask_b32_e32 v124, v249, v64, vcc
	v_cmp_gt_u32_e32 vcc, 2.0, v65
	v_cvt_f32_u32_e32 v65, v65
	s_and_b64 vcc, vcc, s[8:9]
	v_max3_f32 v64, v68, v123, v124
	v_mov_b64_e32 v[70:71], v[38:39]
	v_fma_f32 v65, -v96, v65, v66
	v_cndmask_b32_e32 v125, v249, v65, vcc
	v_subrev_u32_e32 v65, 35, v72
	v_cmp_gt_u32_e32 vcc, 2.0, v65
	v_cvt_f32_u32_e32 v65, v65
	s_and_b64 vcc, vcc, s[8:9]
	v_mov_b64_e32 v[68:69], v[36:37]
	v_fma_f32 v65, -v96, v65, v67
	v_cndmask_b32_e32 v126, v249, v65, vcc
	v_subrev_u32_e32 v65, 48, v72
	v_cmp_gt_u32_e32 vcc, 2.0, v65
	v_cvt_f32_u32_e32 v65, v65
	s_and_b64 vcc, vcc, s[8:9]
	v_max3_f32 v64, v64, v125, v126
	v_fma_f32 v60, -v96, v65, v60
	v_cndmask_b32_e32 v127, v249, v60, vcc
	v_subrev_u32_e32 v60, 49, v72
	v_cmp_gt_u32_e32 vcc, 2.0, v60
	v_cvt_f32_u32_e32 v60, v60
	s_and_b64 vcc, vcc, s[8:9]
	v_fma_f32 v60, -v96, v60, v61
	v_subrev_u32_e32 v61, 50, v72
	v_cndmask_b32_e32 v128, v249, v60, vcc
	v_cmp_gt_u32_e32 vcc, 2.0, v61
	v_cvt_f32_u32_e32 v61, v61
	s_and_b64 vcc, vcc, s[8:9]
	v_max3_f32 v60, v64, v127, v128
	v_mov_b64_e32 v[66:67], v[34:35]
	v_fma_f32 v61, -v96, v61, v62
	v_cndmask_b32_e32 v129, v249, v61, vcc
	v_subrev_u32_e32 v61, 51, v72
	v_cmp_gt_u32_e32 vcc, 2.0, v61
	v_cvt_f32_u32_e32 v61, v61
	s_and_b64 vcc, vcc, s[8:9]
	v_mov_b64_e32 v[74:75], v[42:43]
	v_mov_b64_e32 v[64:65], v[32:33]
	v_fma_f32 v61, -v96, v61, v63
	v_cndmask_b32_e32 v130, v249, v61, vcc
	v_max3_f32 v132, v60, v129, v130
	v_mov_b64_e32 v[62:63], v[30:31]
	v_cmp_gt_f32_e32 vcc, v132, v106
	v_mov_b64_e32 v[60:61], v[28:29]
	v_mov_b64_e32 v[72:73], v[40:41]
	s_cbranch_vccz .LBB0_991
	ds_bpermute_b32 v60, v115, v132
	v_max_f32_e32 v61, v132, v132
	s_waitcnt lgkmcnt(0)
	v_max_f32_e32 v60, v60, v60
	v_max_f32_e32 v60, v61, v60
	ds_bpermute_b32 v61, v114, v60
	s_waitcnt lgkmcnt(0)
	v_max3_f32 v109, v106, v60, v61
	v_sub_f32_e32 v60, v106, v109
	v_exp_f32_e32 v60, v60
	s_nop 0
	v_mul_f32_e32 v131, v107, v60
	v_pk_mul_f32 v[74:75], v[42:43], v[60:61] op_sel_hi:[1,0]
	v_pk_mul_f32 v[72:73], v[40:41], v[60:61] op_sel_hi:[1,0]
	v_pk_mul_f32 v[70:71], v[38:39], v[60:61] op_sel_hi:[1,0]
	v_pk_mul_f32 v[68:69], v[36:37], v[60:61] op_sel_hi:[1,0]
	v_pk_mul_f32 v[66:67], v[34:35], v[60:61] op_sel_hi:[1,0]
	v_pk_mul_f32 v[64:65], v[32:33], v[60:61] op_sel_hi:[1,0]
	v_pk_mul_f32 v[62:63], v[30:31], v[60:61] op_sel_hi:[1,0]
	v_pk_mul_f32 v[60:61], v[28:29], v[60:61] op_sel_hi:[1,0]

.LBB0_992:
	s_and_b64 vcc, exec, s[4:5]
	s_cbranch_vccz .LBB0_996
	s_nop 5
	v_or_b32_e32 v60, v98, v108
	v_sub_u32_e32 v60, v103, v60
	v_cvt_f32_i32_e32 v60, v60
	s_mov_b32 s4, 2.0
	s_mov_b32 s5, 0x40400000
	v_fma_f32 v60, -v96, v60, -v106
	v_cndmask_b32_e64 v68, v249, v60, s[8:9]
	v_pk_fma_f32 v[62:63], v[96:97], s[4:5], v[68:69] op_sel_hi:[1,1,0]
	s_mov_b32 s4, 0x41800000
	s_mov_b32 s5, 0x41880000
	v_fma_f32 v60, 0, v96, v68
	v_add_f32_e32 v61, v96, v68
	v_pk_fma_f32 v[66:67], v[90:91], s[90:91], v[68:69] op_sel_hi:[1,1,0]
	v_pk_fma_f32 v[64:65], v[88:89], s[4:5], v[68:69] op_sel_hi:[1,1,0]
	v_pk_fma_f32 v[78:79], v[90:91], s[92:93], v[68:69] op_sel_hi:[1,1,0]
	v_pk_fma_f32 v[76:77], v[88:89], s[34:35], v[68:69] op_sel_hi:[1,1,0]
	v_pk_fma_f32 v[110:111], v[90:91], s[22:23], v[68:69] op_sel_hi:[1,1,0]
	v_pk_fma_f32 v[108:109], v[88:89], s[72:73], v[68:69] op_sel_hi:[1,1,0]
	s_waitcnt lgkmcnt(7)
	v_mfma_f32_16x16x32_bf16 v[60:63], v[160:163], v[4:7], v[60:63]
	s_waitcnt lgkmcnt(6)
	v_mfma_f32_16x16x32_bf16 v[72:75], v[164:167], v[8:11], v[60:63]
	ds_read_b128 v[196:199], v244
	ds_read_b128 v[200:203], v244 offset:64
	s_waitcnt lgkmcnt(7)
	v_mfma_f32_16x16x32_bf16 v[60:63], v[168:171], v[4:7], v[64:67]
	s_waitcnt lgkmcnt(6)
	v_mfma_f32_16x16x32_bf16 v[68:71], v[172:175], v[8:11], v[60:63]
	ds_read_b128 v[204:207], v244 offset:2304
	ds_read_b128 v[208:211], v244 offset:2368
	s_waitcnt lgkmcnt(7)
	v_mfma_f32_16x16x32_bf16 v[60:63], v[176:179], v[4:7], v[76:79]
	s_waitcnt lgkmcnt(6)
	v_mfma_f32_16x16x32_bf16 v[60:63], v[180:183], v[8:11], v[60:63]
	ds_read_b128 v[212:215], v244 offset:4608
	ds_read_b128 v[216:219], v244 offset:4672
	s_waitcnt lgkmcnt(7)
	v_mfma_f32_16x16x32_bf16 v[64:67], v[184:187], v[4:7], v[108:111]
	s_waitcnt lgkmcnt(6)
	v_mfma_f32_16x16x32_bf16 v[64:67], v[188:191], v[8:11], v[64:67]
	ds_read_b128 v[220:223], v244 offset:6912
	ds_read_b128 v[224:227], v244 offset:6976
	v_max3_f32 v76, v72, s36, v73
	v_max3_f32 v76, v76, v74, v75
	v_max3_f32 v76, v76, v68, v69
	v_max3_f32 v76, v76, v70, v71
	v_max3_f32 v76, v76, v60, v61
	v_max3_f32 v76, v76, v62, v63
	s_nop 1
	v_max3_f32 v76, v76, v64, v65
	v_max3_f32 v76, v76, v66, v67
	v_cmp_lt_f32_e32 vcc, 0, v76
	s_cbranch_vccz .LBB0_995
	ds_bpermute_b32 v77, v115, v76
	v_max_f32_e32 v76, v76, v76
	s_waitcnt lgkmcnt(0)
	v_max_f32_e32 v77, v77, v77
	v_max_f32_e32 v76, v76, v77
	ds_bpermute_b32 v77, v114, v76
	s_waitcnt lgkmcnt(0)
	v_max3_f32 v77, 0, v76, v77
	v_sub_f32_e32 v76, 0, v77
	v_exp_f32_e32 v76, v76
	v_add_f32_e32 v106, v106, v77
	v_mul_f32_e32 v107, v107, v76
	v_pk_mul_f32 v[42:43], v[42:43], v[76:77] op_sel_hi:[1,0]
	v_pk_mul_f32 v[40:41], v[40:41], v[76:77] op_sel_hi:[1,0]
	v_pk_mul_f32 v[38:39], v[38:39], v[76:77] op_sel_hi:[1,0]
	v_pk_mul_f32 v[36:37], v[36:37], v[76:77] op_sel_hi:[1,0]
	v_pk_mul_f32 v[34:35], v[34:35], v[76:77] op_sel_hi:[1,0]
	v_pk_mul_f32 v[32:33], v[32:33], v[76:77] op_sel_hi:[1,0]
	v_pk_mul_f32 v[30:31], v[30:31], v[76:77] op_sel_hi:[1,0]
	v_pk_mul_f32 v[28:29], v[28:29], v[76:77] op_sel_hi:[1,0]
	v_sub_f32_e32 v72, v72, v77
	v_sub_f32_e32 v73, v73, v77
	v_sub_f32_e32 v74, v74, v77
	v_sub_f32_e32 v75, v75, v77
	v_sub_f32_e32 v68, v68, v77
	v_sub_f32_e32 v69, v69, v77
	v_sub_f32_e32 v70, v70, v77
	v_sub_f32_e32 v71, v71, v77
	v_sub_f32_e32 v60, v60, v77
	v_sub_f32_e32 v61, v61, v77
	v_sub_f32_e32 v62, v62, v77
	v_sub_f32_e32 v63, v63, v77
	v_sub_f32_e32 v64, v64, v77
	v_sub_f32_e32 v65, v65, v77
	v_sub_f32_e32 v66, v66, v77
	v_sub_f32_e32 v67, v67, v77
